# v67 + code placement: FNet GEMM phases (FN_CHAN..FN_WO) shifted by 4 bytes
# speedup vs baseline: 1.0065x; 1.0065x over previous
.LBB0_287:
	s_nop 0
	s_add_u32 s0, s56, 0x4d00000
	s_addc_u32 s1, s57, 0
	s_cmp_lt_i32 s58, 3
	s_cselect_b64 s[4:5], -1, 0
	s_and_b64 s[2:3], s[4:5], s[6:7]
	s_andn2_b64 vcc, exec, s[2:3]
	s_cbranch_vccnz .LBB0_320
	v_lshlrev_b32_e32 v1, 4, v0
	v_and_b32_e32 v2, 32, v0
	v_bitop3_b32 v2, v1, v2, 48 bitop3:0x6c
	v_and_or_b32 v141, v0, 64, v2
	v_lshrrev_b32_e32 v2, 1, v0
	v_lshrrev_b32_e32 v4, 5, v0
	v_and_b32_e32 v2, 24, v2
	v_and_b32_e32 v4, 4, v4
	v_bfe_u32 v5, v0, 2, 2
	v_or_b32_e32 v143, 0x2000, v1
	v_bfe_u32 v3, v0, 2, 4
	v_or3_b32 v2, v4, v5, v2
	v_lshrrev_b32_e32 v4, 3, v0
	v_lshrrev_b32_e32 v1, 7, v143
	s_movk_i32 s2, 0x70
	v_and_or_b32 v5, v4, 48, v3
	v_and_or_b32 v3, v1, s2, v3
	s_movk_i32 s2, 0x60
	v_and_or_b32 v144, v1, s2, v2
	s_movk_i32 s2, 0x200
	v_lshlrev_b32_e32 v1, 9, v3
	v_and_or_b32 v142, v4, 32, v2
	v_or_b32_e32 v2, 0xffff0000, v1
	v_cmp_gt_u32_e32 vcc, s2, v0
	s_add_u32 s3, s56, 0x3500000
	v_bfe_u32 v138, v0, 4, 2
	v_cndmask_b32_e32 v1, v2, v1, vcc
	v_lshlrev_b32_e32 v2, 6, v0
	v_lshlrev_b32_e32 v3, 2, v0
	s_addc_u32 s35, s57, 0
	v_lshlrev_b32_e32 v139, 4, v138
	v_and_b32_e32 v2, 0x3c0, v2
	v_and_b32_e32 v3, 32, v3
	v_readfirstlane_b32 s10, v0
	v_lshl_or_b32 v130, v5, 9, v141
	v_or_b32_e32 v132, v1, v141
	v_and_b32_e32 v1, 15, v0
	s_cmpk_gt_i32 s94, 0x7f
	v_bitop3_b32 v140, v139, v3, v2 bitop3:0x36
	s_cbranch_scc1 .LBB0_304
	s_ashr_i32 s11, s94, 3
	s_lshl_b32 s6, s94, 8
	s_and_b32 s12, s6, 0x600
	s_lshl_b32 s6, s11, 8
	s_lshr_b32 s8, s10, 6
	s_and_b32 s14, s94, 1
	s_ashr_i32 s7, s6, 31
	s_lshr_b32 s9, s10, 8
	s_lshl_b32 s2, s8, 10
	s_lshl_b32 s13, s14, 17
	s_lshl_b64 s[6:7], s[6:7], 11
	s_add_u32 s6, s96, s6
	s_addc_u32 s7, s97, s7
	s_waitcnt lgkmcnt(0)
	s_add_u32 s36, s6, s12
	v_lshlrev_b32_e32 v2, 11, v144
	s_addc_u32 s37, s7, 0
	s_add_i32 s16, s2, 0
	v_or_b32_e32 v3, 0xfffc0000, v2
	v_lshl_or_b32 v136, v142, 11, v141
	s_add_i32 m0, s16, 0x10000
	v_cndmask_b32_e32 v2, v3, v2, vcc
	global_load_lds_dwordx4 v136, s[36:37]
	s_add_i32 m0, s16, 0x12000
	v_or_b32_e32 v134, v2, v141
	s_add_u32 s6, s36, 0x40000
	global_load_lds_dwordx4 v134, s[36:37]
	s_addc_u32 s7, s37, 0
	s_add_i32 m0, s16, 0x14000
	v_mov_b32_e32 v137, 0
	global_load_lds_dwordx4 v136, s[6:7]
	s_add_i32 m0, s16, 0x16000
	s_add_u32 s38, s3, s13
	s_addc_u32 s39, s35, 0
	s_add_i32 s17, s16, 0x2000
	global_load_lds_dwordx4 v134, s[6:7]
	s_mov_b32 m0, s16
	s_add_u32 s6, s38, 0x10000
	global_load_lds_dwordx4 v130, s[38:39]
	s_mov_b32 m0, s17
	s_addc_u32 s7, s39, 0
	s_add_i32 s18, s16, 0x4000
	global_load_lds_dwordx4 v132, s[38:39]
	s_mov_b32 m0, s18
	s_add_i32 s19, s16, 0x6000
	global_load_lds_dwordx4 v130, s[6:7]
	s_mov_b32 m0, s19
	v_mov_b32_e32 v135, v137
	global_load_lds_dwordx4 v132, s[6:7]
	v_mov_b32_e32 v131, v137
	v_mov_b32_e32 v133, v137
	s_cmp_eq_u32 s9, 1
	v_lshl_add_u64 v[8:9], s[36:37], 0, v[136:137]
	v_lshl_add_u64 v[6:7], s[36:37], 0, v[134:135]
	v_lshl_add_u64 v[2:3], s[38:39], 0, v[130:131]
	s_cselect_b64 s[6:7], -1, 0
	s_cmp_lg_u32 s9, 1
	v_lshl_add_u64 v[4:5], s[38:39], 0, v[132:133]
	s_cbranch_scc1 .LBB0_291
	s_barrier

.LBB0_580:
	s_nop 0
	s_cmp_lt_i32 s58, 7
	s_cselect_b64 s[10:11], -1, 0
	s_cmp_gt_i32 s59, 6
	s_cselect_b64 s[2:3], -1, 0
	s_and_b64 s[2:3], s[10:11], s[2:3]
	s_andn2_b64 vcc, exec, s[2:3]
	s_cbranch_vccnz .LBB0_681
	s_movk_i32 s2, 0x140
	v_cmp_gt_u32_e32 vcc, s2, v0
	s_waitcnt vmcnt(0) lgkmcnt(0)
	s_barrier
	s_and_saveexec_b64 s[4:5], vcc
	v_add_u32_e32 v1, 0, v0
	v_mov_b32_e32 v2, 0xff
	ds_write_b8 v1, v2
	s_or_b64 exec, exec, s[4:5]
	v_readlane_b32 s2, v249, 2
	v_readlane_b32 s3, v249, 3
	s_cmpk_eq_i32 s2, 0x100
	s_cselect_b64 s[2:3], -1, 0
	v_cmp_gt_u32_e32 vcc, 64, v0
	s_and_b64 s[2:3], s[2:3], vcc
	s_waitcnt lgkmcnt(0)
	s_barrier
	s_and_saveexec_b64 s[4:5], s[2:3]
	s_cbranch_execz .LBB0_585
	v_and_b32_e32 v1, 7, v0
	v_mul_u32_u24_e32 v1, 40, v1
	v_lshrrev_b32_e32 v2, 3, v0
	v_add3_u32 v1, v1, v2, 32
	v_lshrrev_b32_e32 v2, 2, v1
	v_and_b32_e32 v2, 0xf8, v2
	v_sub_u32_e32 v3, 0x50, v2
	v_min_u32_e32 v3, 8, v3
	v_cvt_f32_ubyte0_e32 v4, v3
	v_rcp_iflag_f32_e32 v5, v4
	v_and_b32_e32 v1, 31, v1
	v_cvt_f32_ubyte0_e32 v6, v1
	v_mul_f32_e32 v5, v6, v5
	v_trunc_f32_e32 v5, v5
	v_cvt_u32_f32_e32 v7, v5
	v_fma_f32 v5, -v5, v4, v6
	v_cmp_ge_f32_e64 vcc, |v5|, v4
	s_nop 1
	v_addc_co_u32_e32 v4, vcc, 0, v7, vcc
	v_mul_lo_u16_e32 v3, v4, v3
	v_sub_u16_e32 v1, v1, v3
	v_and_b32_e32 v1, 0xff, v1
	v_and_b32_e32 v3, 0xff, v4
	v_add_lshl_u32 v1, v2, v1, 2
	v_add3_u32 v1, 0, v1, v3
	ds_write_b8 v1, v0
